# transposes: 60+4 load batches (one long round trip per tile, under the 63-op limit) on top of epilogue prefetching
# baseline (speedup 1.0000x reference)
; __device__ __forceinline__ float bf2f(unsigned v) { return __uint_as_float(v << 16); }
; template <bool SRC_BF16> __device__ __forceinline__ void tr_tile(const void* src, int stride, int col0, int myrow, float myscale, bf16_t* dst, float* wl, int lane) {
;     float* scr = wl; int* rws = (int*)(wl + 64 * 65); float* scs = wl + 64 * 65 + 64;
;     rws[lane] = myrow; scs[lane] = myscale;
;     asm volatile("s_waitcnt lgkmcnt(0)" ::: "memory");
; #pragma unroll 32
;     for (int i = 0; i < 64; ++i) { const int r = rws[i]; float v;
;         if (SRC_BF16) v = bf2f(((const bf16_t*)src)[(size_t)r * stride + col0 + lane]); else v = ((const float*)src)[(size_t)r * stride + col0 + lane] * scs[i];
;         scr[i * 65 + lane] = v; }
.LBB0_235:
	s_or_b64 exec, exec, s[6:7]
	v_ashrrev_i32_e32 v20, 1, v5
	v_lshlrev_b32_e32 v5, 6, v5
	v_lshlrev_b32_e32 v9, 7, v20
	v_and_b32_e32 v11, 64, v5
	s_movk_i32 s6, 0x380
	ds_write2st64_b32 v25, v7, v195 offset0:65 offset1:66
	v_and_or_b32 v5, v9, s6, v11
	s_waitcnt lgkmcnt(0)
	v_add_u32_e32 v18, v29, v0
	v_lshlrev_b32_e32 v0, 1, v5
	s_waitcnt vmcnt(0)
	ds_read_b128 v[30:33], v24 offset:16640
	ds_read_b128 v[34:37], v24 offset:16656
	v_lshl_add_u64 v[22:23], s[96:97], 0, v[0:1]
	v_mov_b32_e32 v5, v1
	v_lshl_add_u64 v[22:23], v[22:23], 0, v[4:5]
	s_mov_b64 s[6:7], 0x1000
	v_lshl_add_u64 v[22:23], v[22:23], 0, s[6:7]
	s_waitcnt lgkmcnt(0)
	v_mad_i64_i32 v[38:39], s[6:7], v30, s79, v[22:23]
	v_mad_i64_i32 v[30:31], s[6:7], v31, s79, v[22:23]
	global_load_ushort v66, v[38:39], off
	global_load_ushort v67, v[30:31], off
	v_mad_i64_i32 v[30:31], s[6:7], v32, s79, v[22:23]
	v_mad_i64_i32 v[32:33], s[6:7], v33, s79, v[22:23]
	v_ashrrev_i32_e32 v21, 31, v20
	v_lshlrev_b64 v[20:21], 7, v[20:21]
	v_or_b32_e32 v0, v20, v11
	v_ashrrev_i32_e32 v19, 31, v18
	v_mov_b32_e32 v11, v1
	v_mov_b32_e32 v13, v1
	v_mov_b32_e32 v15, v1
	v_mov_b32_e32 v17, v1
	v_add_u32_e32 v3, s44, v3
	v_add_u32_e32 v29, s8, v29
	global_load_ushort v68, v[30:31], off
	global_load_ushort v69, v[32:33], off
	s_waitcnt lgkmcnt(0)
	v_mad_i64_i32 v[30:31], s[6:7], v34, s79, v[22:23]
	v_mad_i64_i32 v[32:33], s[6:7], v35, s79, v[22:23]
	global_load_ushort v70, v[30:31], off
	global_load_ushort v71, v[32:33], off
	v_mad_i64_i32 v[30:31], s[6:7], v36, s79, v[22:23]
	v_mad_i64_i32 v[32:33], s[6:7], v37, s79, v[22:23]
	global_load_ushort v72, v[30:31], off
	global_load_ushort v73, v[32:33], off
	ds_read_b128 v[30:33], v24 offset:16672
	ds_read_b128 v[34:37], v24 offset:16688
	s_waitcnt lgkmcnt(0)
	v_mad_i64_i32 v[38:39], s[6:7], v30, s79, v[22:23]
	v_mad_i64_i32 v[30:31], s[6:7], v31, s79, v[22:23]
	global_load_ushort v74, v[38:39], off
	global_load_ushort v75, v[30:31], off
	v_mad_i64_i32 v[30:31], s[6:7], v32, s79, v[22:23]
	v_mad_i64_i32 v[32:33], s[6:7], v33, s79, v[22:23]
	global_load_ushort v76, v[30:31], off
	global_load_ushort v77, v[32:33], off
	s_waitcnt lgkmcnt(0)
	v_mad_i64_i32 v[30:31], s[6:7], v34, s79, v[22:23]
	v_mad_i64_i32 v[32:33], s[6:7], v35, s79, v[22:23]
	global_load_ushort v78, v[30:31], off
	global_load_ushort v79, v[32:33], off
	v_mad_i64_i32 v[30:31], s[6:7], v36, s79, v[22:23]
	v_mad_i64_i32 v[32:33], s[6:7], v37, s79, v[22:23]
	global_load_ushort v80, v[30:31], off
	global_load_ushort v81, v[32:33], off
	ds_read_b128 v[30:33], v24 offset:16704
	ds_read_b128 v[34:37], v24 offset:16720
	s_waitcnt lgkmcnt(0)
	v_mad_i64_i32 v[38:39], s[6:7], v30, s79, v[22:23]
	v_mad_i64_i32 v[30:31], s[6:7], v31, s79, v[22:23]
	global_load_ushort v82, v[38:39], off
	global_load_ushort v83, v[30:31], off
	v_mad_i64_i32 v[30:31], s[6:7], v32, s79, v[22:23]
	v_mad_i64_i32 v[32:33], s[6:7], v33, s79, v[22:23]
	global_load_ushort v84, v[30:31], off
	global_load_ushort v85, v[32:33], off
	s_waitcnt lgkmcnt(0)
	v_mad_i64_i32 v[30:31], s[6:7], v34, s79, v[22:23]
	v_mad_i64_i32 v[32:33], s[6:7], v35, s79, v[22:23]
	global_load_ushort v86, v[30:31], off
	global_load_ushort v87, v[32:33], off
	v_mad_i64_i32 v[30:31], s[6:7], v36, s79, v[22:23]
	v_mad_i64_i32 v[32:33], s[6:7], v37, s79, v[22:23]
	global_load_ushort v88, v[30:31], off
	global_load_ushort v89, v[32:33], off
	ds_read_b128 v[30:33], v24 offset:16736
	s_waitcnt lgkmcnt(0)
	v_mad_i64_i32 v[34:35], s[6:7], v30, s79, v[22:23]
	v_mad_i64_i32 v[30:31], s[6:7], v31, s79, v[22:23]
	global_load_ushort v90, v[34:35], off
	global_load_ushort v91, v[30:31], off
	v_mad_i64_i32 v[30:31], s[6:7], v32, s79, v[22:23]
	v_mad_i64_i32 v[32:33], s[6:7], v33, s79, v[22:23]
	global_load_ushort v92, v[30:31], off
	global_load_ushort v93, v[32:33], off
	ds_read_b128 v[30:33], v24 offset:16752
	s_waitcnt lgkmcnt(0)
	v_mad_i64_i32 v[34:35], s[6:7], v30, s79, v[22:23]
	v_mad_i64_i32 v[30:31], s[6:7], v31, s79, v[22:23]
	global_load_ushort v94, v[34:35], off
	global_load_ushort v95, v[30:31], off
	v_mad_i64_i32 v[30:31], s[6:7], v32, s79, v[22:23]
	v_mad_i64_i32 v[32:33], s[6:7], v33, s79, v[22:23]
	global_load_ushort v96, v[30:31], off
	global_load_ushort v97, v[32:33], off
	ds_read_b128 v[30:33], v24 offset:16768
	s_waitcnt lgkmcnt(0)
	v_mad_i64_i32 v[34:35], s[6:7], v30, s79, v[22:23]
	v_mad_i64_i32 v[30:31], s[6:7], v31, s79, v[22:23]
	global_load_ushort v98, v[34:35], off
	global_load_ushort v99, v[30:31], off
	v_mad_i64_i32 v[30:31], s[6:7], v32, s79, v[22:23]
	v_mad_i64_i32 v[32:33], s[6:7], v33, s79, v[22:23]
	global_load_ushort v100, v[30:31], off
	global_load_ushort v101, v[32:33], off
	ds_read_b128 v[30:33], v24 offset:16784
	s_waitcnt lgkmcnt(0)
	v_mad_i64_i32 v[34:35], s[6:7], v30, s79, v[22:23]
	v_mad_i64_i32 v[30:31], s[6:7], v31, s79, v[22:23]
	global_load_ushort v102, v[34:35], off
	global_load_ushort v103, v[30:31], off
	v_mad_i64_i32 v[30:31], s[6:7], v32, s79, v[22:23]
	v_mad_i64_i32 v[32:33], s[6:7], v33, s79, v[22:23]
	global_load_ushort v104, v[30:31], off
	global_load_ushort v105, v[32:33], off
	ds_read_b128 v[30:33], v24 offset:16800
	s_waitcnt lgkmcnt(0)
	v_mad_i64_i32 v[34:35], s[6:7], v30, s79, v[22:23]
	v_mad_i64_i32 v[30:31], s[6:7], v31, s79, v[22:23]
	global_load_ushort v106, v[34:35], off
	global_load_ushort v107, v[30:31], off
	v_mad_i64_i32 v[30:31], s[6:7], v32, s79, v[22:23]
	v_mad_i64_i32 v[32:33], s[6:7], v33, s79, v[22:23]
	global_load_ushort v108, v[30:31], off
	global_load_ushort v109, v[32:33], off
	ds_read_b128 v[30:33], v24 offset:16816
	s_waitcnt lgkmcnt(0)
; __device__ __forceinline__ float bf2f(unsigned v) { return __uint_as_float(v << 16); }
; template <bool SRC_BF16> __device__ __forceinline__ void tr_tile(const void* src, int stride, int col0, int myrow, float myscale, bf16_t* dst, float* wl, int lane) {
;     ...
;     for (int i = 0; i < 64; ++i) { const int r = rws[i]; float v;
;         if (SRC_BF16) v = bf2f(((const bf16_t*)src)[(size_t)r * stride + col0 + lane]); else v = ((const float*)src)[(size_t)r * stride + col0 + lane] * scs[i];
;         scr[i * 65 + lane] = v; }
	v_mad_i64_i32 v[34:35], s[6:7], v30, s79, v[22:23]
	v_mad_i64_i32 v[30:31], s[6:7], v31, s79, v[22:23]
	global_load_ushort v110, v[34:35], off
	global_load_ushort v111, v[30:31], off
	v_mad_i64_i32 v[30:31], s[6:7], v32, s79, v[22:23]
	v_mad_i64_i32 v[32:33], s[6:7], v33, s79, v[22:23]
	global_load_ushort v112, v[30:31], off
	global_load_ushort v113, v[32:33], off
	ds_read_b128 v[30:33], v24 offset:16832
	s_waitcnt lgkmcnt(0)
	v_mad_i64_i32 v[34:35], s[6:7], v30, s79, v[22:23]
	v_mad_i64_i32 v[30:31], s[6:7], v31, s79, v[22:23]
	global_load_ushort v114, v[34:35], off
	global_load_ushort v115, v[30:31], off
	v_mad_i64_i32 v[30:31], s[6:7], v32, s79, v[22:23]
	v_mad_i64_i32 v[32:33], s[6:7], v33, s79, v[22:23]
	global_load_ushort v116, v[30:31], off
	global_load_ushort v117, v[32:33], off
	ds_read_b128 v[30:33], v24 offset:16848
	s_waitcnt lgkmcnt(0)
	v_mad_i64_i32 v[34:35], s[6:7], v30, s79, v[22:23]
	v_mad_i64_i32 v[30:31], s[6:7], v31, s79, v[22:23]
	global_load_ushort v118, v[34:35], off
	global_load_ushort v119, v[30:31], off
	v_mad_i64_i32 v[30:31], s[6:7], v32, s79, v[22:23]
	v_mad_i64_i32 v[32:33], s[6:7], v33, s79, v[22:23]
	global_load_ushort v120, v[30:31], off
	global_load_ushort v121, v[32:33], off
	ds_read_b128 v[30:33], v24 offset:16864
	s_waitcnt lgkmcnt(0)
	v_mad_i64_i32 v[34:35], s[6:7], v30, s79, v[22:23]
	v_mad_i64_i32 v[30:31], s[6:7], v31, s79, v[22:23]
	global_load_ushort v122, v[34:35], off
	global_load_ushort v123, v[30:31], off
	v_mad_i64_i32 v[30:31], s[6:7], v32, s79, v[22:23]
	v_mad_i64_i32 v[32:33], s[6:7], v33, s79, v[22:23]
	global_load_ushort v124, v[30:31], off
	global_load_ushort v125, v[32:33], off
	ds_read_b128 v[30:33], v24 offset:16880
	s_waitcnt lgkmcnt(0)
	v_mad_i64_i32 v[34:35], s[6:7], v30, s79, v[22:23]
	v_mad_i64_i32 v[30:31], s[6:7], v31, s79, v[22:23]
	s_waitcnt vmcnt(56)
	v_lshlrev_b32_e32 v66, 16, v66
	v_lshlrev_b32_e32 v67, 16, v67
	v_lshlrev_b32_e32 v68, 16, v68
	v_lshlrev_b32_e32 v69, 16, v69
	ds_write_b32 v25, v66 offset:0
	ds_write_b32 v25, v67 offset:260
	ds_write_b32 v25, v68 offset:520
	ds_write_b32 v25, v69 offset:780
	s_waitcnt vmcnt(52)
	v_lshlrev_b32_e32 v70, 16, v70
	v_lshlrev_b32_e32 v71, 16, v71
	v_lshlrev_b32_e32 v72, 16, v72
	v_lshlrev_b32_e32 v73, 16, v73
	ds_write_b32 v25, v70 offset:1040
	ds_write_b32 v25, v71 offset:1300
	ds_write_b32 v25, v72 offset:1560
	ds_write_b32 v25, v73 offset:1820
	s_waitcnt vmcnt(48)
	v_lshlrev_b32_e32 v74, 16, v74
	v_lshlrev_b32_e32 v75, 16, v75
	v_lshlrev_b32_e32 v76, 16, v76
	v_lshlrev_b32_e32 v77, 16, v77
	ds_write_b32 v25, v74 offset:2080
	ds_write_b32 v25, v75 offset:2340
	ds_write_b32 v25, v76 offset:2600
	ds_write_b32 v25, v77 offset:2860
	s_waitcnt vmcnt(44)
	v_lshlrev_b32_e32 v78, 16, v78
	v_lshlrev_b32_e32 v79, 16, v79
	v_lshlrev_b32_e32 v80, 16, v80
	v_lshlrev_b32_e32 v81, 16, v81
	ds_write_b32 v25, v78 offset:3120
	ds_write_b32 v25, v79 offset:3380
	ds_write_b32 v25, v80 offset:3640
	ds_write_b32 v25, v81 offset:3900
	s_waitcnt vmcnt(40)
	v_lshlrev_b32_e32 v82, 16, v82
	v_lshlrev_b32_e32 v83, 16, v83
	v_lshlrev_b32_e32 v84, 16, v84
	v_lshlrev_b32_e32 v85, 16, v85
	ds_write_b32 v25, v82 offset:4160
	ds_write_b32 v25, v83 offset:4420
	ds_write_b32 v25, v84 offset:4680
	ds_write_b32 v25, v85 offset:4940
	s_waitcnt vmcnt(36)
	v_lshlrev_b32_e32 v86, 16, v86
	v_lshlrev_b32_e32 v87, 16, v87
	v_lshlrev_b32_e32 v88, 16, v88
	v_lshlrev_b32_e32 v89, 16, v89
	ds_write_b32 v25, v86 offset:5200
	ds_write_b32 v25, v87 offset:5460
	ds_write_b32 v25, v88 offset:5720
	ds_write_b32 v25, v89 offset:5980
	s_waitcnt vmcnt(32)
	v_lshlrev_b32_e32 v90, 16, v90
	v_lshlrev_b32_e32 v91, 16, v91
	v_lshlrev_b32_e32 v92, 16, v92
	v_lshlrev_b32_e32 v93, 16, v93
	ds_write_b32 v25, v90 offset:6240
	ds_write_b32 v25, v91 offset:6500
	ds_write_b32 v25, v92 offset:6760
	ds_write_b32 v25, v93 offset:7020
	s_waitcnt vmcnt(28)
	v_lshlrev_b32_e32 v94, 16, v94
	v_lshlrev_b32_e32 v95, 16, v95
	v_lshlrev_b32_e32 v96, 16, v96
	v_lshlrev_b32_e32 v97, 16, v97
	ds_write_b32 v25, v94 offset:7280
	ds_write_b32 v25, v95 offset:7540
	ds_write_b32 v25, v96 offset:7800
	ds_write_b32 v25, v97 offset:8060
	s_waitcnt vmcnt(24)
	v_lshlrev_b32_e32 v98, 16, v98
	v_lshlrev_b32_e32 v99, 16, v99
	v_lshlrev_b32_e32 v100, 16, v100
	v_lshlrev_b32_e32 v101, 16, v101
	ds_write_b32 v25, v98 offset:8320
	ds_write_b32 v25, v99 offset:8580
	ds_write_b32 v25, v100 offset:8840
	ds_write_b32 v25, v101 offset:9100
	s_waitcnt vmcnt(20)
	v_lshlrev_b32_e32 v102, 16, v102
	v_lshlrev_b32_e32 v103, 16, v103
	v_lshlrev_b32_e32 v104, 16, v104
	v_lshlrev_b32_e32 v105, 16, v105
	ds_write_b32 v25, v102 offset:9360
	ds_write_b32 v25, v103 offset:9620
	ds_write_b32 v25, v104 offset:9880
	ds_write_b32 v25, v105 offset:10140
	s_waitcnt vmcnt(16)
	v_lshlrev_b32_e32 v106, 16, v106
	v_lshlrev_b32_e32 v107, 16, v107
	v_lshlrev_b32_e32 v108, 16, v108
	v_lshlrev_b32_e32 v109, 16, v109
	ds_write_b32 v25, v106 offset:10400
	ds_write_b32 v25, v107 offset:10660
	ds_write_b32 v25, v108 offset:10920
	ds_write_b32 v25, v109 offset:11180
	s_waitcnt vmcnt(12)
	v_lshlrev_b32_e32 v110, 16, v110
	v_lshlrev_b32_e32 v111, 16, v111
	v_lshlrev_b32_e32 v112, 16, v112
	v_lshlrev_b32_e32 v113, 16, v113
	ds_write_b32 v25, v110 offset:11440
	ds_write_b32 v25, v111 offset:11700
	ds_write_b32 v25, v112 offset:11960
	ds_write_b32 v25, v113 offset:12220
	s_waitcnt vmcnt(8)
	v_lshlrev_b32_e32 v114, 16, v114
	v_lshlrev_b32_e32 v115, 16, v115
	v_lshlrev_b32_e32 v116, 16, v116
	v_lshlrev_b32_e32 v117, 16, v117
	ds_write_b32 v25, v114 offset:12480
	ds_write_b32 v25, v115 offset:12740
	ds_write_b32 v25, v116 offset:13000
	ds_write_b32 v25, v117 offset:13260
	s_waitcnt vmcnt(4)
; __device__ __forceinline__ float bf2f(unsigned v) { return __uint_as_float(v << 16); }
; __device__ __forceinline__ unsigned pk2(float lo, float hi) { return pg8::cvt_pk_bf16(lo, hi); }
; template <bool SRC_BF16> __device__ __forceinline__ void tr_tile(const void* src, int stride, int col0, int myrow, float myscale, bf16_t* dst, float* wl, int lane) {
;     ...
;     for (int i = 0; i < 64; ++i) { const int r = rws[i]; float v;
;         if (SRC_BF16) v = bf2f(((const bf16_t*)src)[(size_t)r * stride + col0 + lane]); else v = ((const float*)src)[(size_t)r * stride + col0 + lane] * scs[i];
;         scr[i * 65 + lane] = v; }
;     asm volatile("s_waitcnt vmcnt(0) lgkmcnt(0)" ::: "memory");
;     const int pb = lane & 7, cl = lane >> 3, ib = 32 * (pb >> 2) + 16 * ((pb >> 1) & 1) + 4 * (pb & 1);
; #pragma unroll
;     for (int k = 0; k < 8; ++k) { const int j = cl + 8 * k; float v[8];
; #pragma unroll
;         for (int jj = 0; jj < 8; ++jj) v[jj] = scr[(ib + 8 * (jj >> 2) + (jj & 3)) * 65 + j];
;         u32x4 w; w.x = pk2(v[0], v[1]); w.y = pk2(v[2], v[3]); w.z = pk2(v[4], v[5]); w.w = pk2(v[6], v[7]);
;         *(u32x4*)(dst + (size_t)j * KVL + 8 * pb) = w; }
;     asm volatile("s_waitcnt lgkmcnt(0)" ::: "memory");
	v_lshlrev_b32_e32 v118, 16, v118
	v_lshlrev_b32_e32 v119, 16, v119
	v_lshlrev_b32_e32 v120, 16, v120
	v_lshlrev_b32_e32 v121, 16, v121
	ds_write_b32 v25, v118 offset:13520
	ds_write_b32 v25, v119 offset:13780
	ds_write_b32 v25, v120 offset:14040
	ds_write_b32 v25, v121 offset:14300
	s_waitcnt vmcnt(0)
	v_lshlrev_b32_e32 v122, 16, v122
	v_lshlrev_b32_e32 v123, 16, v123
	v_lshlrev_b32_e32 v124, 16, v124
	v_lshlrev_b32_e32 v125, 16, v125
	ds_write_b32 v25, v122 offset:14560
	ds_write_b32 v25, v123 offset:14820
	ds_write_b32 v25, v124 offset:15080
	ds_write_b32 v25, v125 offset:15340
	s_waitcnt lgkmcnt(0)
	global_load_ushort v126, v[34:35], off
	global_load_ushort v127, v[30:31], off
	v_mad_i64_i32 v[30:31], s[6:7], v32, s79, v[22:23]
	v_mad_i64_i32 v[22:23], s[6:7], v33, s79, v[22:23]
	global_load_ushort v128, v[30:31], off
	global_load_ushort v129, v[22:23], off
	v_mov_b64_e32 v[22:23], s[90:91]
	v_mad_u64_u32 v[22:23], s[6:7], v0, s66, v[22:23]
	v_add_u32_e32 v0, 0x800, v28
	v_mad_i32_i24 v23, v21, s66, v23
	v_lshl_add_u64 v[18:19], v[18:19], 1, v[22:23]
	s_mov_b32 s6, 0x11000
	s_waitcnt vmcnt(0)
	v_lshlrev_b32_e32 v126, 16, v126
	v_lshlrev_b32_e32 v127, 16, v127
	v_lshlrev_b32_e32 v128, 16, v128
	v_lshlrev_b32_e32 v129, 16, v129
	ds_write_b32 v25, v126 offset:15600
	ds_write_b32 v25, v127 offset:15860
	ds_write_b32 v25, v128 offset:16120
	ds_write_b32 v25, v129 offset:16380
	s_waitcnt vmcnt(0) lgkmcnt(0)
	ds_read2_b32 v[30:31], v28 offset0:65 offset1:73
	ds_read2_b32 v[32:33], v28 offset1:8
	ds_read2_b32 v[34:35], v28 offset0:130 offset1:138
	ds_read2_b32 v[36:37], v28 offset0:195 offset1:203
	ds_read2_b32 v[38:39], v0 offset0:8 offset1:16
	ds_read2_b32 v[40:41], v0 offset0:73 offset1:81
	ds_read2_b32 v[42:43], v0 offset0:138 offset1:146
	ds_read2_b32 v[44:45], v0 offset0:203 offset1:211
	v_mov_b32_e32 v7, v1
	v_lshl_add_u64 v[22:23], v[18:19], 0, v[6:7]
	v_mov_b32_e32 v9, v1
	v_lshl_add_u64 v[46:47], v[22:23], 0, v[8:9]
	s_waitcnt lgkmcnt(6)
	v_cvt_pk_bf16_f32 v18, v32, v30
	s_waitcnt lgkmcnt(4)
	v_cvt_pk_bf16_f32 v19, v34, v36
	s_waitcnt lgkmcnt(2)
	v_cvt_pk_bf16_f32 v20, v38, v40
	s_waitcnt lgkmcnt(0)
	v_cvt_pk_bf16_f32 v21, v42, v44
	v_add_co_u32_e32 v30, vcc, s6, v46
	global_store_dwordx4 v[46:47], v[18:21], off
	s_movk_i32 s6, 0x87f
	s_nop 0
	v_cvt_pk_bf16_f32 v18, v33, v31
	v_cvt_pk_bf16_f32 v19, v35, v37
	v_cvt_pk_bf16_f32 v20, v39, v41
	v_cvt_pk_bf16_f32 v21, v43, v45
	v_addc_co_u32_e32 v31, vcc, 0, v47, vcc
	global_store_dwordx4 v[30:31], v[18:21], off
	ds_read2_b32 v[30:31], v28 offset0:81 offset1:89
	ds_read2_b32 v[32:33], v28 offset0:16 offset1:24
	ds_read2_b32 v[34:35], v28 offset0:146 offset1:154
	ds_read2_b32 v[36:37], v28 offset0:211 offset1:219
	ds_read2_b32 v[38:39], v0 offset0:24 offset1:32
	ds_read2_b32 v[40:41], v0 offset0:89 offset1:97
	ds_read2_b32 v[42:43], v0 offset0:154 offset1:162
	ds_read2_b32 v[44:45], v0 offset0:219 offset1:227
	v_add_co_u32_e32 v48, vcc, s76, v46
	s_waitcnt lgkmcnt(6)
	v_cvt_pk_bf16_f32 v18, v32, v30
	v_addc_co_u32_e32 v49, vcc, 0, v47, vcc
	s_waitcnt lgkmcnt(4)
	v_cvt_pk_bf16_f32 v19, v34, v36
	s_waitcnt lgkmcnt(2)
	v_cvt_pk_bf16_f32 v20, v38, v40
	s_waitcnt lgkmcnt(0)
	v_cvt_pk_bf16_f32 v21, v42, v44
	v_add_co_u32_e32 v30, vcc, s17, v46
	global_store_dwordx4 v[48:49], v[18:21], off
	s_nop 1
	v_cvt_pk_bf16_f32 v18, v33, v31
	v_cvt_pk_bf16_f32 v19, v35, v37
	v_cvt_pk_bf16_f32 v20, v39, v41
	v_cvt_pk_bf16_f32 v21, v43, v45
	v_addc_co_u32_e32 v31, vcc, 0, v47, vcc
	global_store_dwordx4 v[30:31], v[18:21], off
	ds_read2_b32 v[30:31], v28 offset0:97 offset1:105
	ds_read2_b32 v[32:33], v28 offset0:32 offset1:40
	ds_read2_b32 v[34:35], v28 offset0:162 offset1:170
	ds_read2_b32 v[36:37], v28 offset0:227 offset1:235
	ds_read2_b32 v[38:39], v0 offset0:40 offset1:48
	ds_read2_b32 v[40:41], v0 offset0:105 offset1:113
	ds_read2_b32 v[42:43], v0 offset0:170 offset1:178
	ds_read2_b32 v[44:45], v0 offset0:235 offset1:243
	s_waitcnt lgkmcnt(6)
	v_cvt_pk_bf16_f32 v18, v32, v30
	s_waitcnt lgkmcnt(4)
	v_cvt_pk_bf16_f32 v19, v34, v36
	s_waitcnt lgkmcnt(2)
	v_cvt_pk_bf16_f32 v20, v38, v40
	v_lshl_add_u64 v[46:47], v[22:23], 0, v[10:11]
	s_waitcnt lgkmcnt(0)
	v_cvt_pk_bf16_f32 v21, v42, v44
	global_store_dwordx4 v[46:47], v[18:21], off
	v_lshl_add_u64 v[46:47], v[22:23], 0, v[14:15]
	v_cmp_lt_i32_e32 vcc, s6, v3
	v_cvt_pk_bf16_f32 v18, v33, v31
	v_cvt_pk_bf16_f32 v19, v35, v37
	v_cvt_pk_bf16_f32 v20, v39, v41
	v_cvt_pk_bf16_f32 v21, v43, v45
	v_lshl_add_u64 v[30:31], v[22:23], 0, v[12:13]
	global_store_dwordx4 v[30:31], v[18:21], off
	ds_read2_b32 v[30:31], v28 offset0:48 offset1:56
	ds_read2_b32 v[32:33], v28 offset0:113 offset1:121
	ds_read2_b32 v[34:35], v28 offset0:178 offset1:186
	ds_read2_b32 v[36:37], v28 offset0:243 offset1:251
	ds_read2_b32 v[38:39], v0 offset0:56 offset1:64
	ds_read2_b32 v[40:41], v0 offset0:121 offset1:129
	ds_read2_b32 v[42:43], v0 offset0:186 offset1:194
	v_add_u32_e32 v0, 0xa00, v28
	ds_read2_b32 v[44:45], v0 offset0:123 offset1:131
	s_waitcnt lgkmcnt(6)
	v_cvt_pk_bf16_f32 v18, v30, v32
	s_waitcnt lgkmcnt(4)
	v_cvt_pk_bf16_f32 v19, v34, v36
	s_waitcnt lgkmcnt(2)
	v_cvt_pk_bf16_f32 v20, v38, v40
	v_lshl_add_u64 v[22:23], v[22:23], 0, v[16:17]
	s_waitcnt lgkmcnt(0)
	v_cvt_pk_bf16_f32 v21, v42, v44
	global_store_dwordx4 v[46:47], v[18:21], off
	s_or_b64 s[4:5], vcc, s[4:5]
	s_nop 0
	v_cvt_pk_bf16_f32 v18, v31, v33
	v_cvt_pk_bf16_f32 v19, v35, v37
	v_cvt_pk_bf16_f32 v20, v39, v41
	v_cvt_pk_bf16_f32 v21, v43, v45
	global_store_dwordx4 v[22:23], v[18:21], off
	s_waitcnt lgkmcnt(0)
	s_andn2_b64 exec, exec, s[4:5]
	s_cbranch_execz .LBB0_240

; __device__ __forceinline__ float bf2f(unsigned v) { return __uint_as_float(v << 16); }
; template <bool SRC_BF16> __device__ __forceinline__ void tr_tile(const void* src, int stride, int col0, int myrow, float myscale, bf16_t* dst, float* wl, int lane) {
;     float* scr = wl; int* rws = (int*)(wl + 64 * 65); float* scs = wl + 64 * 65 + 64;
;     rws[lane] = myrow; scs[lane] = myscale;
;     asm volatile("s_waitcnt lgkmcnt(0)" ::: "memory");
; #pragma unroll 32
;     for (int i = 0; i < 64; ++i) { const int r = rws[i]; float v;
;         if (SRC_BF16) v = bf2f(((const bf16_t*)src)[(size_t)r * stride + col0 + lane]); else v = ((const float*)src)[(size_t)r * stride + col0 + lane] * scs[i];
;         scr[i * 65 + lane] = v; }
.LBB0_313:
	s_or_b64 exec, exec, s[0:1]
	v_and_b32_e32 v19, 15, v3
	v_lshlrev_b32_e32 v3, 6, v5
	v_lshlrev_b32_e32 v0, 4, v0
	v_or3_b32 v28, v3, v0, v19
	v_ashrrev_i32_e32 v29, 31, v28
	v_lshl_add_u64 v[28:29], v[28:29], 2, s[22:23]
	global_load_dword v0, v[28:29], off
	v_ashrrev_i32_e32 v3, 31, v2
	v_add_u32_e32 v26, v17, v4
	v_lshlrev_b64 v[28:29], 10, v[2:3]
	v_ashrrev_i32_e32 v27, 31, v26
	s_waitcnt vmcnt(0)
	ds_write2st64_b32 v13, v5, v0 offset0:65 offset1:66
	s_waitcnt lgkmcnt(0)
	s_waitcnt vmcnt(0)
	ds_read_b128 v[2:5], v11 offset:16640
	ds_read_b128 v[32:35], v11 offset:16656
	v_lshlrev_b32_e32 v0, 8, v19
	v_lshl_add_u64 v[30:31], v[20:21], 0, v[0:1]
	v_lshl_or_b32 v0, v19, 6, v28
	s_waitcnt lgkmcnt(0)
	v_mad_i64_i32 v[36:37], s[0:1], v2, s78, v[30:31]
	v_mad_i64_i32 v[2:3], s[0:1], v3, s78, v[30:31]
	global_load_dword v66, v[36:37], off
	global_load_dword v67, v[2:3], off
	s_waitcnt lgkmcnt(0)
	v_mad_i64_i32 v[2:3], s[0:1], v4, s78, v[30:31]
	v_mad_i64_i32 v[4:5], s[0:1], v5, s78, v[30:31]
	global_load_dword v68, v[2:3], off
	s_nop 0
	global_load_dword v69, v[4:5], off
	v_mad_i64_i32 v[4:5], s[0:1], v33, s78, v[30:31]
	v_mad_i64_i32 v[2:3], s[0:1], v32, s78, v[30:31]
	global_load_dword v70, v[2:3], off
	global_load_dword v71, v[4:5], off
	s_waitcnt lgkmcnt(0)
	v_mad_i64_i32 v[2:3], s[0:1], v34, s78, v[30:31]
	v_mad_i64_i32 v[32:33], s[0:1], v35, s78, v[30:31]
	global_load_dword v72, v[2:3], off
	s_nop 0
	global_load_dword v73, v[32:33], off
	ds_read_b128 v[2:5], v11 offset:16672
	ds_read_b128 v[32:35], v11 offset:16688
	s_waitcnt lgkmcnt(0)
	v_mad_i64_i32 v[36:37], s[0:1], v2, s78, v[30:31]
	v_mad_i64_i32 v[2:3], s[0:1], v3, s78, v[30:31]
	global_load_dword v74, v[36:37], off
	global_load_dword v75, v[2:3], off
	s_waitcnt lgkmcnt(0)
	v_mad_i64_i32 v[2:3], s[0:1], v4, s78, v[30:31]
	v_mad_i64_i32 v[4:5], s[0:1], v5, s78, v[30:31]
	global_load_dword v76, v[2:3], off
	s_nop 0
	global_load_dword v77, v[4:5], off
	v_mad_i64_i32 v[4:5], s[0:1], v33, s78, v[30:31]
	v_mad_i64_i32 v[2:3], s[0:1], v32, s78, v[30:31]
	global_load_dword v78, v[2:3], off
	global_load_dword v79, v[4:5], off
	s_waitcnt lgkmcnt(0)
	v_mad_i64_i32 v[2:3], s[0:1], v34, s78, v[30:31]
	v_mad_i64_i32 v[32:33], s[0:1], v35, s78, v[30:31]
	global_load_dword v80, v[2:3], off
	s_nop 0
	global_load_dword v81, v[32:33], off
	ds_read_b128 v[2:5], v11 offset:16704
	ds_read_b128 v[32:35], v11 offset:16720
	s_waitcnt lgkmcnt(0)
	v_mad_i64_i32 v[36:37], s[0:1], v2, s78, v[30:31]
	v_mad_i64_i32 v[2:3], s[0:1], v3, s78, v[30:31]
	global_load_dword v82, v[36:37], off
	global_load_dword v83, v[2:3], off
	s_waitcnt lgkmcnt(0)
	v_mad_i64_i32 v[2:3], s[0:1], v4, s78, v[30:31]
	v_mad_i64_i32 v[4:5], s[0:1], v5, s78, v[30:31]
	global_load_dword v84, v[2:3], off
	s_nop 0
	global_load_dword v85, v[4:5], off
	v_mad_i64_i32 v[4:5], s[0:1], v33, s78, v[30:31]
	v_mad_i64_i32 v[2:3], s[0:1], v32, s78, v[30:31]
	global_load_dword v86, v[2:3], off
	global_load_dword v87, v[4:5], off
	s_waitcnt lgkmcnt(0)
	v_mad_i64_i32 v[2:3], s[0:1], v34, s78, v[30:31]
	v_mad_i64_i32 v[32:33], s[0:1], v35, s78, v[30:31]
	global_load_dword v88, v[2:3], off
	s_nop 0
	global_load_dword v89, v[32:33], off
	ds_read_b128 v[2:5], v11 offset:16736
	s_waitcnt lgkmcnt(0)
	v_mad_i64_i32 v[32:33], s[0:1], v2, s78, v[30:31]
	v_mad_i64_i32 v[2:3], s[0:1], v3, s78, v[30:31]
	global_load_dword v90, v[32:33], off
	global_load_dword v91, v[2:3], off
	s_waitcnt lgkmcnt(0)
	v_mad_i64_i32 v[2:3], s[0:1], v4, s78, v[30:31]
	v_mad_i64_i32 v[4:5], s[0:1], v5, s78, v[30:31]
	global_load_dword v92, v[2:3], off
	s_nop 0
	global_load_dword v93, v[4:5], off
	ds_read_b128 v[2:5], v11 offset:16752
	s_waitcnt lgkmcnt(0)
	v_mad_i64_i32 v[32:33], s[0:1], v2, s78, v[30:31]
	v_mad_i64_i32 v[2:3], s[0:1], v3, s78, v[30:31]
	global_load_dword v94, v[32:33], off
	global_load_dword v95, v[2:3], off
	s_waitcnt lgkmcnt(0)
	v_mad_i64_i32 v[2:3], s[0:1], v4, s78, v[30:31]
	v_mad_i64_i32 v[4:5], s[0:1], v5, s78, v[30:31]
	global_load_dword v96, v[2:3], off
	s_nop 0
	global_load_dword v97, v[4:5], off
	ds_read_b128 v[2:5], v11 offset:16768
	s_waitcnt lgkmcnt(0)
	v_mad_i64_i32 v[32:33], s[0:1], v2, s78, v[30:31]
	v_mad_i64_i32 v[2:3], s[0:1], v3, s78, v[30:31]
	global_load_dword v98, v[32:33], off
	global_load_dword v99, v[2:3], off
	s_waitcnt lgkmcnt(0)
	v_mad_i64_i32 v[2:3], s[0:1], v4, s78, v[30:31]
	v_mad_i64_i32 v[4:5], s[0:1], v5, s78, v[30:31]
	global_load_dword v100, v[2:3], off
	s_nop 0
	global_load_dword v101, v[4:5], off
	ds_read_b128 v[2:5], v11 offset:16784
	s_waitcnt lgkmcnt(0)
	v_mad_i64_i32 v[32:33], s[0:1], v2, s78, v[30:31]
	v_mad_i64_i32 v[2:3], s[0:1], v3, s78, v[30:31]
	global_load_dword v102, v[32:33], off
	global_load_dword v103, v[2:3], off
	s_waitcnt lgkmcnt(0)
	v_mad_i64_i32 v[2:3], s[0:1], v4, s78, v[30:31]
	v_mad_i64_i32 v[4:5], s[0:1], v5, s78, v[30:31]
	global_load_dword v104, v[2:3], off
	s_nop 0
	global_load_dword v105, v[4:5], off
	ds_read_b128 v[2:5], v11 offset:16800
	s_waitcnt lgkmcnt(0)
	v_mad_i64_i32 v[32:33], s[0:1], v2, s78, v[30:31]
	v_mad_i64_i32 v[2:3], s[0:1], v3, s78, v[30:31]
	global_load_dword v106, v[32:33], off
	global_load_dword v107, v[2:3], off
	s_waitcnt lgkmcnt(0)
	v_mad_i64_i32 v[2:3], s[0:1], v4, s78, v[30:31]
	v_mad_i64_i32 v[4:5], s[0:1], v5, s78, v[30:31]
	global_load_dword v108, v[2:3], off
	s_nop 0
	global_load_dword v109, v[4:5], off
	ds_read_b128 v[2:5], v11 offset:16816
	s_waitcnt lgkmcnt(0)
	v_mad_i64_i32 v[32:33], s[0:1], v2, s78, v[30:31]
	v_mad_i64_i32 v[2:3], s[0:1], v3, s78, v[30:31]
	global_load_dword v110, v[32:33], off
	global_load_dword v111, v[2:3], off
	s_waitcnt lgkmcnt(0)
; __device__ __forceinline__ float bf2f(unsigned v) { return __uint_as_float(v << 16); }
; template <bool SRC_BF16> __device__ __forceinline__ void tr_tile(const void* src, int stride, int col0, int myrow, float myscale, bf16_t* dst, float* wl, int lane) {
;     ...
;     for (int i = 0; i < 64; ++i) { const int r = rws[i]; float v;
;         if (SRC_BF16) v = bf2f(((const bf16_t*)src)[(size_t)r * stride + col0 + lane]); else v = ((const float*)src)[(size_t)r * stride + col0 + lane] * scs[i];
;         scr[i * 65 + lane] = v; }
	v_mad_i64_i32 v[2:3], s[0:1], v4, s78, v[30:31]
	v_mad_i64_i32 v[4:5], s[0:1], v5, s78, v[30:31]
	global_load_dword v112, v[2:3], off
	s_nop 0
	global_load_dword v113, v[4:5], off
	ds_read_b128 v[2:5], v11 offset:16832
	s_waitcnt lgkmcnt(0)
	v_mad_i64_i32 v[32:33], s[0:1], v2, s78, v[30:31]
	v_mad_i64_i32 v[2:3], s[0:1], v3, s78, v[30:31]
	global_load_dword v114, v[32:33], off
	global_load_dword v115, v[2:3], off
	s_waitcnt lgkmcnt(0)
	v_mad_i64_i32 v[2:3], s[0:1], v4, s78, v[30:31]
	v_mad_i64_i32 v[4:5], s[0:1], v5, s78, v[30:31]
	global_load_dword v116, v[2:3], off
	s_nop 0
	global_load_dword v117, v[4:5], off
	ds_read_b128 v[2:5], v11 offset:16848
	s_waitcnt lgkmcnt(0)
	v_mad_i64_i32 v[32:33], s[0:1], v2, s78, v[30:31]
	v_mad_i64_i32 v[2:3], s[0:1], v3, s78, v[30:31]
	global_load_dword v118, v[32:33], off
	global_load_dword v119, v[2:3], off
	s_waitcnt lgkmcnt(0)
	v_mad_i64_i32 v[2:3], s[0:1], v4, s78, v[30:31]
	v_mad_i64_i32 v[4:5], s[0:1], v5, s78, v[30:31]
	global_load_dword v120, v[2:3], off
	s_nop 0
	global_load_dword v121, v[4:5], off
	ds_read_b128 v[2:5], v11 offset:16864
	s_waitcnt lgkmcnt(0)
	v_mad_i64_i32 v[32:33], s[0:1], v2, s78, v[30:31]
	v_mad_i64_i32 v[2:3], s[0:1], v3, s78, v[30:31]
	global_load_dword v122, v[32:33], off
	global_load_dword v123, v[2:3], off
	s_waitcnt lgkmcnt(0)
	v_mad_i64_i32 v[2:3], s[0:1], v4, s78, v[30:31]
	v_mad_i64_i32 v[4:5], s[0:1], v5, s78, v[30:31]
	global_load_dword v124, v[2:3], off
	s_nop 0
	global_load_dword v125, v[4:5], off
	ds_read_b128 v[32:35], v11 offset:16880
	s_waitcnt lgkmcnt(0)
	v_mad_i64_i32 v[2:3], s[0:1], v32, s78, v[30:31]
	v_mad_i64_i32 v[4:5], s[0:1], v33, s78, v[30:31]
	ds_read_b128 v[130:133], v11 offset:16896
	ds_read_b128 v[134:137], v11 offset:16912
	s_waitcnt vmcnt(56) lgkmcnt(1)
	v_pk_mul_f32 v[66:67], v[66:67], v[130:131]
	v_pk_mul_f32 v[68:69], v[68:69], v[132:133]
	ds_write_b32 v13, v66 offset:0
	ds_write_b32 v13, v67 offset:260
	ds_write_b32 v13, v68 offset:520
	ds_write_b32 v13, v69 offset:780
	ds_read_b128 v[130:133], v11 offset:16928
	s_waitcnt vmcnt(52) lgkmcnt(1)
	v_pk_mul_f32 v[70:71], v[70:71], v[134:135]
	v_pk_mul_f32 v[72:73], v[72:73], v[136:137]
	ds_write_b32 v13, v70 offset:1040
	ds_write_b32 v13, v71 offset:1300
	ds_write_b32 v13, v72 offset:1560
	ds_write_b32 v13, v73 offset:1820
	ds_read_b128 v[134:137], v11 offset:16944
	s_waitcnt vmcnt(48) lgkmcnt(1)
	v_pk_mul_f32 v[74:75], v[74:75], v[130:131]
	v_pk_mul_f32 v[76:77], v[76:77], v[132:133]
	ds_write_b32 v13, v74 offset:2080
	ds_write_b32 v13, v75 offset:2340
	ds_write_b32 v13, v76 offset:2600
	ds_write_b32 v13, v77 offset:2860
	ds_read_b128 v[130:133], v11 offset:16960
	s_waitcnt vmcnt(44) lgkmcnt(1)
	v_pk_mul_f32 v[78:79], v[78:79], v[134:135]
	v_pk_mul_f32 v[80:81], v[80:81], v[136:137]
	ds_write_b32 v13, v78 offset:3120
	ds_write_b32 v13, v79 offset:3380
	ds_write_b32 v13, v80 offset:3640
	ds_write_b32 v13, v81 offset:3900
	ds_read_b128 v[134:137], v11 offset:16976
	s_waitcnt vmcnt(40) lgkmcnt(1)
	v_pk_mul_f32 v[82:83], v[82:83], v[130:131]
	v_pk_mul_f32 v[84:85], v[84:85], v[132:133]
	ds_write_b32 v13, v82 offset:4160
	ds_write_b32 v13, v83 offset:4420
	ds_write_b32 v13, v84 offset:4680
	ds_write_b32 v13, v85 offset:4940
	ds_read_b128 v[130:133], v11 offset:16992
	s_waitcnt vmcnt(36) lgkmcnt(1)
	v_pk_mul_f32 v[86:87], v[86:87], v[134:135]
	v_pk_mul_f32 v[88:89], v[88:89], v[136:137]
	ds_write_b32 v13, v86 offset:5200
	ds_write_b32 v13, v87 offset:5460
	ds_write_b32 v13, v88 offset:5720
	ds_write_b32 v13, v89 offset:5980
	ds_read_b128 v[134:137], v11 offset:17008
	s_waitcnt vmcnt(32) lgkmcnt(1)
	v_pk_mul_f32 v[90:91], v[90:91], v[130:131]
	v_pk_mul_f32 v[92:93], v[92:93], v[132:133]
	ds_write_b32 v13, v90 offset:6240
	ds_write_b32 v13, v91 offset:6500
	ds_write_b32 v13, v92 offset:6760
	ds_write_b32 v13, v93 offset:7020
	ds_read_b128 v[130:133], v11 offset:17024
	s_waitcnt vmcnt(28) lgkmcnt(1)
	v_pk_mul_f32 v[94:95], v[94:95], v[134:135]
	v_pk_mul_f32 v[96:97], v[96:97], v[136:137]
	ds_write_b32 v13, v94 offset:7280
	ds_write_b32 v13, v95 offset:7540
	ds_write_b32 v13, v96 offset:7800
	ds_write_b32 v13, v97 offset:8060
	ds_read_b128 v[134:137], v11 offset:17040
	s_waitcnt vmcnt(24) lgkmcnt(1)
	v_pk_mul_f32 v[98:99], v[98:99], v[130:131]
	v_pk_mul_f32 v[100:101], v[100:101], v[132:133]
	ds_write_b32 v13, v98 offset:8320
	ds_write_b32 v13, v99 offset:8580
	ds_write_b32 v13, v100 offset:8840
	ds_write_b32 v13, v101 offset:9100
	ds_read_b128 v[130:133], v11 offset:17056
	s_waitcnt vmcnt(20) lgkmcnt(1)
	v_pk_mul_f32 v[102:103], v[102:103], v[134:135]
	v_pk_mul_f32 v[104:105], v[104:105], v[136:137]
	ds_write_b32 v13, v102 offset:9360
	ds_write_b32 v13, v103 offset:9620
	ds_write_b32 v13, v104 offset:9880
	ds_write_b32 v13, v105 offset:10140
	ds_read_b128 v[134:137], v11 offset:17072
	s_waitcnt vmcnt(16) lgkmcnt(1)
	v_pk_mul_f32 v[106:107], v[106:107], v[130:131]
	v_pk_mul_f32 v[108:109], v[108:109], v[132:133]
	ds_write_b32 v13, v106 offset:10400
	ds_write_b32 v13, v107 offset:10660
	ds_write_b32 v13, v108 offset:10920
	ds_write_b32 v13, v109 offset:11180
	ds_read_b128 v[130:133], v11 offset:17088
	s_waitcnt vmcnt(12) lgkmcnt(1)
	v_pk_mul_f32 v[110:111], v[110:111], v[134:135]
	v_pk_mul_f32 v[112:113], v[112:113], v[136:137]
	ds_write_b32 v13, v110 offset:11440
	ds_write_b32 v13, v111 offset:11700
	ds_write_b32 v13, v112 offset:11960
	ds_write_b32 v13, v113 offset:12220
	ds_read_b128 v[134:137], v11 offset:17104
	s_waitcnt vmcnt(8) lgkmcnt(1)
; __device__ __forceinline__ float bf2f(unsigned v) { return __uint_as_float(v << 16); }
; __device__ __forceinline__ unsigned pk2(float lo, float hi) { return pg8::cvt_pk_bf16(lo, hi); }
; template <bool SRC_BF16> __device__ __forceinline__ void tr_tile(const void* src, int stride, int col0, int myrow, float myscale, bf16_t* dst, float* wl, int lane) {
;     ...
;     for (int i = 0; i < 64; ++i) { const int r = rws[i]; float v;
;         if (SRC_BF16) v = bf2f(((const bf16_t*)src)[(size_t)r * stride + col0 + lane]); else v = ((const float*)src)[(size_t)r * stride + col0 + lane] * scs[i];
;         scr[i * 65 + lane] = v; }
;     asm volatile("s_waitcnt vmcnt(0) lgkmcnt(0)" ::: "memory");
;     const int pb = lane & 7, cl = lane >> 3, ib = 32 * (pb >> 2) + 16 * ((pb >> 1) & 1) + 4 * (pb & 1);
; #pragma unroll
;     for (int k = 0; k < 8; ++k) { const int j = cl + 8 * k; float v[8];
; #pragma unroll
;         for (int jj = 0; jj < 8; ++jj) v[jj] = scr[(ib + 8 * (jj >> 2) + (jj & 3)) * 65 + j];
;         u32x4 w; w.x = pk2(v[0], v[1]); w.y = pk2(v[2], v[3]); w.z = pk2(v[4], v[5]); w.w = pk2(v[6], v[7]);
;         *(u32x4*)(dst + (size_t)j * KVL + 8 * pb) = w; }
	v_pk_mul_f32 v[114:115], v[114:115], v[130:131]
	v_pk_mul_f32 v[116:117], v[116:117], v[132:133]
	ds_write_b32 v13, v114 offset:12480
	ds_write_b32 v13, v115 offset:12740
	ds_write_b32 v13, v116 offset:13000
	ds_write_b32 v13, v117 offset:13260
	ds_read_b128 v[130:133], v11 offset:17120
	s_waitcnt vmcnt(4) lgkmcnt(1)
	v_pk_mul_f32 v[118:119], v[118:119], v[134:135]
	v_pk_mul_f32 v[120:121], v[120:121], v[136:137]
	ds_write_b32 v13, v118 offset:13520
	ds_write_b32 v13, v119 offset:13780
	ds_write_b32 v13, v120 offset:14040
	ds_write_b32 v13, v121 offset:14300
	s_waitcnt vmcnt(0) lgkmcnt(0)
	v_pk_mul_f32 v[122:123], v[122:123], v[130:131]
	v_pk_mul_f32 v[124:125], v[124:125], v[132:133]
	ds_write_b32 v13, v122 offset:14560
	ds_write_b32 v13, v123 offset:14820
	ds_write_b32 v13, v124 offset:15080
	ds_write_b32 v13, v125 offset:15340
	s_waitcnt lgkmcnt(0)
	global_load_dword v126, v[2:3], off
	global_load_dword v127, v[4:5], off
	s_waitcnt lgkmcnt(0)
	v_mad_i64_i32 v[2:3], s[0:1], v34, s78, v[30:31]
	v_mad_i64_i32 v[30:31], s[0:1], v35, s78, v[30:31]
	global_load_dword v128, v[2:3], off
	s_nop 0
	global_load_dword v129, v[30:31], off
	v_mov_b64_e32 v[2:3], s[36:37]
	v_mad_u64_u32 v[2:3], s[0:1], v0, s66, v[2:3]
	ds_read_b128 v[134:137], v11 offset:17136
	s_waitcnt vmcnt(0) lgkmcnt(0)
	v_pk_mul_f32 v[126:127], v[126:127], v[134:135]
	v_pk_mul_f32 v[128:129], v[128:129], v[136:137]
	ds_write_b32 v13, v126 offset:15600
	ds_write_b32 v13, v127 offset:15860
	ds_write_b32 v13, v128 offset:16120
	ds_write_b32 v13, v129 offset:16380
	s_waitcnt vmcnt(0) lgkmcnt(0)
	v_add_u32_e32 v19, 0x800, v15
	v_mad_i32_i24 v3, v29, s66, v3
	ds_read2_b32 v[28:29], v15 offset0:65 offset1:73
	ds_read2_b32 v[30:31], v15 offset1:8
	ds_read2_b32 v[32:33], v15 offset0:130 offset1:138
	ds_read2_b32 v[34:35], v15 offset0:195 offset1:203
	ds_read2_b32 v[36:37], v19 offset0:8 offset1:16
	ds_read2_b32 v[38:39], v19 offset0:73 offset1:81
	ds_read2_b32 v[40:41], v19 offset0:138 offset1:146
	ds_read2_b32 v[42:43], v19 offset0:203 offset1:211
	v_lshl_add_u64 v[2:3], v[26:27], 1, v[2:3]
	v_lshlrev_b32_e32 v0, 1, v8
	v_lshl_add_u64 v[26:27], v[2:3], 0, v[0:1]
	v_lshlrev_b32_e32 v0, 1, v10
	v_lshl_add_u64 v[44:45], v[26:27], 0, v[0:1]
	s_mov_b32 s0, 0x11000
	s_waitcnt lgkmcnt(6)
	v_cvt_pk_bf16_f32 v2, v30, v28
	s_waitcnt lgkmcnt(4)
	v_cvt_pk_bf16_f32 v3, v32, v34
	s_waitcnt lgkmcnt(2)
	v_cvt_pk_bf16_f32 v4, v36, v38
	s_waitcnt lgkmcnt(0)
	v_cvt_pk_bf16_f32 v5, v40, v42
	v_add_co_u32_e32 v28, vcc, s0, v44
	global_store_dwordx4 v[44:45], v[2:5], off
	v_lshlrev_b32_e32 v0, 1, v12
	s_nop 0
	v_cvt_pk_bf16_f32 v2, v31, v29
	v_cvt_pk_bf16_f32 v3, v33, v35
	v_cvt_pk_bf16_f32 v4, v37, v39
	v_cvt_pk_bf16_f32 v5, v41, v43
	v_addc_co_u32_e32 v29, vcc, 0, v45, vcc
	global_store_dwordx4 v[28:29], v[2:5], off
	ds_read2_b32 v[28:29], v15 offset0:81 offset1:89
	ds_read2_b32 v[30:31], v15 offset0:16 offset1:24
	ds_read2_b32 v[32:33], v15 offset0:146 offset1:154
	ds_read2_b32 v[34:35], v15 offset0:211 offset1:219
	ds_read2_b32 v[36:37], v19 offset0:24 offset1:32
	ds_read2_b32 v[38:39], v19 offset0:89 offset1:97
	ds_read2_b32 v[40:41], v19 offset0:154 offset1:162
	ds_read2_b32 v[42:43], v19 offset0:219 offset1:227
	v_add_co_u32_e32 v46, vcc, s60, v44
	s_waitcnt lgkmcnt(6)
	v_cvt_pk_bf16_f32 v2, v30, v28
	v_addc_co_u32_e32 v47, vcc, 0, v45, vcc
	s_waitcnt lgkmcnt(4)
	v_cvt_pk_bf16_f32 v3, v32, v34
	s_waitcnt lgkmcnt(2)
	v_cvt_pk_bf16_f32 v4, v36, v38
	s_waitcnt lgkmcnt(0)
	v_cvt_pk_bf16_f32 v5, v40, v42
	v_add_co_u32_e32 v28, vcc, s25, v44
	global_store_dwordx4 v[46:47], v[2:5], off
	s_nop 1
	v_cvt_pk_bf16_f32 v2, v31, v29
	v_cvt_pk_bf16_f32 v3, v33, v35
	v_cvt_pk_bf16_f32 v4, v37, v39
	v_cvt_pk_bf16_f32 v5, v41, v43
	v_addc_co_u32_e32 v29, vcc, 0, v45, vcc
	global_store_dwordx4 v[28:29], v[2:5], off
	ds_read2_b32 v[28:29], v15 offset0:97 offset1:105
	ds_read2_b32 v[30:31], v15 offset0:32 offset1:40
	ds_read2_b32 v[32:33], v15 offset0:162 offset1:170
	ds_read2_b32 v[34:35], v15 offset0:227 offset1:235
	ds_read2_b32 v[36:37], v19 offset0:40 offset1:48
	ds_read2_b32 v[38:39], v19 offset0:105 offset1:113
	ds_read2_b32 v[40:41], v19 offset0:170 offset1:178
	ds_read2_b32 v[42:43], v19 offset0:235 offset1:243
	s_waitcnt lgkmcnt(6)
	v_cvt_pk_bf16_f32 v2, v30, v28
	s_waitcnt lgkmcnt(4)
	v_cvt_pk_bf16_f32 v3, v32, v34
	s_waitcnt lgkmcnt(2)
	v_cvt_pk_bf16_f32 v4, v36, v38
	v_lshl_add_u64 v[44:45], v[26:27], 0, v[0:1]
	s_waitcnt lgkmcnt(0)
	v_cvt_pk_bf16_f32 v5, v40, v42
	v_lshlrev_b32_e32 v0, 1, v14
	global_store_dwordx4 v[44:45], v[2:5], off
	s_nop 1
	v_cvt_pk_bf16_f32 v2, v31, v29
	v_cvt_pk_bf16_f32 v3, v33, v35
	v_cvt_pk_bf16_f32 v4, v37, v39
	v_cvt_pk_bf16_f32 v5, v41, v43
	v_lshl_add_u64 v[28:29], v[26:27], 0, v[0:1]
	global_store_dwordx4 v[28:29], v[2:5], off
	v_add_u32_e32 v0, 0xa00, v15
	ds_read2_b32 v[28:29], v15 offset0:48 offset1:56
	ds_read2_b32 v[30:31], v15 offset0:113 offset1:121
	ds_read2_b32 v[32:33], v15 offset0:178 offset1:186
	ds_read2_b32 v[34:35], v15 offset0:243 offset1:251
	ds_read2_b32 v[36:37], v19 offset0:56 offset1:64
	ds_read2_b32 v[38:39], v19 offset0:121 offset1:129
	ds_read2_b32 v[40:41], v19 offset0:186 offset1:194
	ds_read2_b32 v[42:43], v0 offset0:123 offset1:131
	v_lshlrev_b32_e32 v0, 1, v16
	s_waitcnt lgkmcnt(6)
	v_cvt_pk_bf16_f32 v2, v28, v30
	s_waitcnt lgkmcnt(4)
	v_cvt_pk_bf16_f32 v3, v32, v34
	s_waitcnt lgkmcnt(2)
	v_cvt_pk_bf16_f32 v4, v36, v38
	s_waitcnt lgkmcnt(0)
	v_cvt_pk_bf16_f32 v5, v40, v42
	v_lshl_add_u64 v[44:45], v[26:27], 0, v[0:1]
	v_lshlrev_b32_e32 v0, 1, v18
	global_store_dwordx4 v[44:45], v[2:5], off
	v_lshl_add_u64 v[26:27], v[26:27], 0, v[0:1]
	s_nop 0
	v_cvt_pk_bf16_f32 v2, v29, v31
	v_cvt_pk_bf16_f32 v3, v33, v35
	v_cvt_pk_bf16_f32 v4, v37, v39
	v_cvt_pk_bf16_f32 v5, v41, v43
	global_store_dwordx4 v[26:27], v[2:5], off
	s_waitcnt lgkmcnt(0)

; __device__ __forceinline__ float bf2f(unsigned v) { return __uint_as_float(v << 16); }
; template <bool SRC_BF16> __device__ __forceinline__ void tr_tile(const void* src, int stride, int col0, int myrow, float myscale, bf16_t* dst, float* wl, int lane) {
;     float* scr = wl; int* rws = (int*)(wl + 64 * 65); float* scs = wl + 64 * 65 + 64;
;     rws[lane] = myrow; scs[lane] = myscale;
;     asm volatile("s_waitcnt lgkmcnt(0)" ::: "memory");
; #pragma unroll 32
;     for (int i = 0; i < 64; ++i) { const int r = rws[i]; float v;
;         if (SRC_BF16) v = bf2f(((const bf16_t*)src)[(size_t)r * stride + col0 + lane]); else v = ((const float*)src)[(size_t)r * stride + col0 + lane] * scs[i];
; __device__ __forceinline__ void prep2_phase(const Args& a, float* lds) {
;     ...
;           } else { const int t2 = tI - 4 * 16 * 68; const int pt = t2 % 68, rest = t2 / 68, nh = rest & 1, bdg = rest >> 1, g = bdg & 1, dir = (bdg >> 1) & 1, b = bdg >> 2;
;               tr_tile<false>(xbc, 1536, 1024 + g * 128 + 64 * nh, seq_row(b, dir, 64 * pt + lane), 1.f, BT + ((size_t)bdg * 128 + 64 * nh) * KVL + 64 * pt, wl, lane); }
.LBB0_315:
	s_movk_i32 s0, 0x10ff
	v_cmp_lt_i32_e32 vcc, s0, v9
	s_and_saveexec_b64 s[0:1], vcc
	s_xor_b64 s[8:9], exec, s[0:1]
	s_cbranch_execz .LBB0_321
	v_add_u16_e32 v0, 0xef00, v9
	v_mul_u32_u24_e32 v3, 0xf0f1, v0
	v_lshrrev_b32_e32 v2, 22, v3
	v_mul_lo_u16_e32 v4, 0x44, v2
	v_sub_u16_e32 v4, v0, v4
	v_lshlrev_b16_e32 v19, 6, v4
	v_cmp_lt_u16_e64 s[0:1], 3, v4
	v_and_b32_e32 v4, 4, v2
	v_lshrrev_b32_e32 v0, 25, v3
	v_or_b32_e32 v3, v6, v19
	v_cmp_eq_u32_e32 vcc, 0, v4
	s_and_saveexec_b64 s[14:15], s[0:1]
	s_xor_b64 s[0:1], exec, s[14:15]
	v_add_u32_e32 v4, 0xffffff00, v3
	v_sub_u32_e32 v3, 0x10ff, v3
	v_cndmask_b32_e32 v3, v3, v4, vcc
	v_lshl_add_u32 v4, v0, 12, v3
	s_andn2_saveexec_b64 s[0:1], s[0:1]
	v_sub_u32_e32 v4, 0xff, v3
	v_lshlrev_b32_e32 v0, 8, v0
	v_cndmask_b32_e32 v3, v4, v3, vcc
	v_add3_u32 v4, v0, v3, s70
	s_or_b64 exec, exec, s[0:1]
	v_lshlrev_b32_e32 v0, 8, v2
	v_and_b32_e32 v0, 0x300, v0
	ds_write2st64_b32 v13, v4, v195 offset0:65 offset1:66
	v_lshl_add_u64 v[4:5], s[26:27], 0, v[0:1]
	v_mov_b32_e32 v25, v1
	s_waitcnt lgkmcnt(0)
	v_lshl_add_u64 v[4:5], v[4:5], 0, v[24:25]
	s_mov_b64 s[0:1], 0x1000
	v_lshl_add_u64 v[26:27], v[4:5], 0, s[0:1]
	v_mul_u32_u24_e32 v0, 0x88000, v2
	s_waitcnt vmcnt(0)
	ds_read_b128 v[2:5], v11 offset:16640
	ds_read_b128 v[28:31], v11 offset:16656
	s_waitcnt lgkmcnt(0)
	v_mad_i64_i32 v[32:33], s[0:1], v2, s78, v[26:27]
	v_mad_i64_i32 v[2:3], s[0:1], v3, s78, v[26:27]
	global_load_dword v66, v[32:33], off
	global_load_dword v67, v[2:3], off
	s_waitcnt lgkmcnt(0)
	v_mad_i64_i32 v[2:3], s[0:1], v4, s78, v[26:27]
	v_mad_i64_i32 v[4:5], s[0:1], v5, s78, v[26:27]
	global_load_dword v68, v[2:3], off
	s_nop 0
	global_load_dword v69, v[4:5], off
	v_mad_i64_i32 v[4:5], s[0:1], v29, s78, v[26:27]
	v_mad_i64_i32 v[2:3], s[0:1], v28, s78, v[26:27]
	global_load_dword v70, v[2:3], off
	global_load_dword v71, v[4:5], off
	s_waitcnt lgkmcnt(0)
	v_mad_i64_i32 v[2:3], s[0:1], v30, s78, v[26:27]
	v_mad_i64_i32 v[28:29], s[0:1], v31, s78, v[26:27]
	global_load_dword v72, v[2:3], off
	s_nop 0
	global_load_dword v73, v[28:29], off
	ds_read_b128 v[2:5], v11 offset:16672
	ds_read_b128 v[28:31], v11 offset:16688
	s_waitcnt lgkmcnt(0)
	v_mad_i64_i32 v[32:33], s[0:1], v2, s78, v[26:27]
	v_mad_i64_i32 v[2:3], s[0:1], v3, s78, v[26:27]
	global_load_dword v74, v[32:33], off
	global_load_dword v75, v[2:3], off
	s_waitcnt lgkmcnt(0)
	v_mad_i64_i32 v[2:3], s[0:1], v4, s78, v[26:27]
	v_mad_i64_i32 v[4:5], s[0:1], v5, s78, v[26:27]
	global_load_dword v76, v[2:3], off
	s_nop 0
	global_load_dword v77, v[4:5], off
	v_mad_i64_i32 v[4:5], s[0:1], v29, s78, v[26:27]
	v_mad_i64_i32 v[2:3], s[0:1], v28, s78, v[26:27]
	global_load_dword v78, v[2:3], off
	global_load_dword v79, v[4:5], off
	s_waitcnt lgkmcnt(0)
	v_mad_i64_i32 v[2:3], s[0:1], v30, s78, v[26:27]
	v_mad_i64_i32 v[28:29], s[0:1], v31, s78, v[26:27]
	global_load_dword v80, v[2:3], off
	s_nop 0
	global_load_dword v81, v[28:29], off
	ds_read_b128 v[2:5], v11 offset:16704
	ds_read_b128 v[28:31], v11 offset:16720
	s_waitcnt lgkmcnt(0)
	v_mad_i64_i32 v[32:33], s[0:1], v2, s78, v[26:27]
	v_mad_i64_i32 v[2:3], s[0:1], v3, s78, v[26:27]
	global_load_dword v82, v[32:33], off
	global_load_dword v83, v[2:3], off
	s_waitcnt lgkmcnt(0)
	v_mad_i64_i32 v[2:3], s[0:1], v4, s78, v[26:27]
	v_mad_i64_i32 v[4:5], s[0:1], v5, s78, v[26:27]
	global_load_dword v84, v[2:3], off
	s_nop 0
	global_load_dword v85, v[4:5], off
	v_mad_i64_i32 v[4:5], s[0:1], v29, s78, v[26:27]
	v_mad_i64_i32 v[2:3], s[0:1], v28, s78, v[26:27]
	global_load_dword v86, v[2:3], off
	global_load_dword v87, v[4:5], off
	s_waitcnt lgkmcnt(0)
	v_mad_i64_i32 v[2:3], s[0:1], v30, s78, v[26:27]
	v_mad_i64_i32 v[28:29], s[0:1], v31, s78, v[26:27]
	global_load_dword v88, v[2:3], off
	s_nop 0
	global_load_dword v89, v[28:29], off
	ds_read_b128 v[2:5], v11 offset:16736
	s_waitcnt lgkmcnt(0)
	v_mad_i64_i32 v[28:29], s[0:1], v2, s78, v[26:27]
	v_mad_i64_i32 v[2:3], s[0:1], v3, s78, v[26:27]
	global_load_dword v90, v[28:29], off
	global_load_dword v91, v[2:3], off
	s_waitcnt lgkmcnt(0)
	v_mad_i64_i32 v[2:3], s[0:1], v4, s78, v[26:27]
	v_mad_i64_i32 v[4:5], s[0:1], v5, s78, v[26:27]
	global_load_dword v92, v[2:3], off
	s_nop 0
	global_load_dword v93, v[4:5], off
	ds_read_b128 v[2:5], v11 offset:16752
	s_waitcnt lgkmcnt(0)
	v_mad_i64_i32 v[28:29], s[0:1], v2, s78, v[26:27]
	v_mad_i64_i32 v[2:3], s[0:1], v3, s78, v[26:27]
	global_load_dword v94, v[28:29], off
	global_load_dword v95, v[2:3], off
	s_waitcnt lgkmcnt(0)
	v_mad_i64_i32 v[2:3], s[0:1], v4, s78, v[26:27]
	v_mad_i64_i32 v[4:5], s[0:1], v5, s78, v[26:27]
	global_load_dword v96, v[2:3], off
	s_nop 0
	global_load_dword v97, v[4:5], off
	ds_read_b128 v[2:5], v11 offset:16768
	s_waitcnt lgkmcnt(0)
	v_mad_i64_i32 v[28:29], s[0:1], v2, s78, v[26:27]
	v_mad_i64_i32 v[2:3], s[0:1], v3, s78, v[26:27]
	global_load_dword v98, v[28:29], off
	global_load_dword v99, v[2:3], off
	s_waitcnt lgkmcnt(0)
	v_mad_i64_i32 v[2:3], s[0:1], v4, s78, v[26:27]
	v_mad_i64_i32 v[4:5], s[0:1], v5, s78, v[26:27]
	global_load_dword v100, v[2:3], off
	s_nop 0
	global_load_dword v101, v[4:5], off
	ds_read_b128 v[2:5], v11 offset:16784
	s_waitcnt lgkmcnt(0)
	v_mad_i64_i32 v[28:29], s[0:1], v2, s78, v[26:27]
	v_mad_i64_i32 v[2:3], s[0:1], v3, s78, v[26:27]
	global_load_dword v102, v[28:29], off
	global_load_dword v103, v[2:3], off
	s_waitcnt lgkmcnt(0)
	v_mad_i64_i32 v[2:3], s[0:1], v4, s78, v[26:27]
	v_mad_i64_i32 v[4:5], s[0:1], v5, s78, v[26:27]
	global_load_dword v104, v[2:3], off
	s_nop 0
	global_load_dword v105, v[4:5], off
	ds_read_b128 v[2:5], v11 offset:16800
	s_waitcnt lgkmcnt(0)
; __device__ __forceinline__ float bf2f(unsigned v) { return __uint_as_float(v << 16); }
; template <bool SRC_BF16> __device__ __forceinline__ void tr_tile(const void* src, int stride, int col0, int myrow, float myscale, bf16_t* dst, float* wl, int lane) {
;     ...
;     for (int i = 0; i < 64; ++i) { const int r = rws[i]; float v;
;         if (SRC_BF16) v = bf2f(((const bf16_t*)src)[(size_t)r * stride + col0 + lane]); else v = ((const float*)src)[(size_t)r * stride + col0 + lane] * scs[i];
;         scr[i * 65 + lane] = v; }
	v_mad_i64_i32 v[28:29], s[0:1], v2, s78, v[26:27]
	v_mad_i64_i32 v[2:3], s[0:1], v3, s78, v[26:27]
	global_load_dword v106, v[28:29], off
	global_load_dword v107, v[2:3], off
	s_waitcnt lgkmcnt(0)
	v_mad_i64_i32 v[2:3], s[0:1], v4, s78, v[26:27]
	v_mad_i64_i32 v[4:5], s[0:1], v5, s78, v[26:27]
	global_load_dword v108, v[2:3], off
	s_nop 0
	global_load_dword v109, v[4:5], off
	ds_read_b128 v[2:5], v11 offset:16816
	s_waitcnt lgkmcnt(0)
	v_mad_i64_i32 v[28:29], s[0:1], v2, s78, v[26:27]
	v_mad_i64_i32 v[2:3], s[0:1], v3, s78, v[26:27]
	global_load_dword v110, v[28:29], off
	global_load_dword v111, v[2:3], off
	s_waitcnt lgkmcnt(0)
	v_mad_i64_i32 v[2:3], s[0:1], v4, s78, v[26:27]
	v_mad_i64_i32 v[4:5], s[0:1], v5, s78, v[26:27]
	global_load_dword v112, v[2:3], off
	s_nop 0
	global_load_dword v113, v[4:5], off
	ds_read_b128 v[2:5], v11 offset:16832
	s_waitcnt lgkmcnt(0)
	v_mad_i64_i32 v[28:29], s[0:1], v2, s78, v[26:27]
	v_mad_i64_i32 v[2:3], s[0:1], v3, s78, v[26:27]
	global_load_dword v114, v[28:29], off
	global_load_dword v115, v[2:3], off
	s_waitcnt lgkmcnt(0)
	v_mad_i64_i32 v[2:3], s[0:1], v4, s78, v[26:27]
	v_mad_i64_i32 v[4:5], s[0:1], v5, s78, v[26:27]
	global_load_dword v116, v[2:3], off
	s_nop 0
	global_load_dword v117, v[4:5], off
	ds_read_b128 v[2:5], v11 offset:16848
	s_waitcnt lgkmcnt(0)
	v_mad_i64_i32 v[28:29], s[0:1], v2, s78, v[26:27]
	v_mad_i64_i32 v[2:3], s[0:1], v3, s78, v[26:27]
	global_load_dword v118, v[28:29], off
	global_load_dword v119, v[2:3], off
	s_waitcnt lgkmcnt(0)
	v_mad_i64_i32 v[2:3], s[0:1], v4, s78, v[26:27]
	v_mad_i64_i32 v[4:5], s[0:1], v5, s78, v[26:27]
	global_load_dword v120, v[2:3], off
	s_nop 0
	global_load_dword v121, v[4:5], off
	ds_read_b128 v[2:5], v11 offset:16864
	s_waitcnt lgkmcnt(0)
	v_mad_i64_i32 v[28:29], s[0:1], v2, s78, v[26:27]
	v_mad_i64_i32 v[2:3], s[0:1], v3, s78, v[26:27]
	global_load_dword v122, v[28:29], off
	global_load_dword v123, v[2:3], off
	s_waitcnt lgkmcnt(0)
	v_mad_i64_i32 v[2:3], s[0:1], v4, s78, v[26:27]
	v_mad_i64_i32 v[4:5], s[0:1], v5, s78, v[26:27]
	global_load_dword v124, v[2:3], off
	s_nop 0
	global_load_dword v125, v[4:5], off
	ds_read_b128 v[28:31], v11 offset:16880
	s_waitcnt lgkmcnt(0)
	v_mad_i64_i32 v[2:3], s[0:1], v28, s78, v[26:27]
	v_mad_i64_i32 v[4:5], s[0:1], v29, s78, v[26:27]
	ds_read_b128 v[130:133], v11 offset:16896
	ds_read_b128 v[134:137], v11 offset:16912
	s_waitcnt vmcnt(56) lgkmcnt(1)
	v_pk_mul_f32 v[66:67], v[66:67], v[130:131]
	v_pk_mul_f32 v[68:69], v[68:69], v[132:133]
	ds_write_b32 v13, v66 offset:0
	ds_write_b32 v13, v67 offset:260
	ds_write_b32 v13, v68 offset:520
	ds_write_b32 v13, v69 offset:780
	ds_read_b128 v[130:133], v11 offset:16928
	s_waitcnt vmcnt(52) lgkmcnt(1)
	v_pk_mul_f32 v[70:71], v[70:71], v[134:135]
	v_pk_mul_f32 v[72:73], v[72:73], v[136:137]
	ds_write_b32 v13, v70 offset:1040
	ds_write_b32 v13, v71 offset:1300
	ds_write_b32 v13, v72 offset:1560
	ds_write_b32 v13, v73 offset:1820
	ds_read_b128 v[134:137], v11 offset:16944
	s_waitcnt vmcnt(48) lgkmcnt(1)
	v_pk_mul_f32 v[74:75], v[74:75], v[130:131]
	v_pk_mul_f32 v[76:77], v[76:77], v[132:133]
	ds_write_b32 v13, v74 offset:2080
	ds_write_b32 v13, v75 offset:2340
	ds_write_b32 v13, v76 offset:2600
	ds_write_b32 v13, v77 offset:2860
	ds_read_b128 v[130:133], v11 offset:16960
	s_waitcnt vmcnt(44) lgkmcnt(1)
	v_pk_mul_f32 v[78:79], v[78:79], v[134:135]
	v_pk_mul_f32 v[80:81], v[80:81], v[136:137]
	ds_write_b32 v13, v78 offset:3120
	ds_write_b32 v13, v79 offset:3380
	ds_write_b32 v13, v80 offset:3640
	ds_write_b32 v13, v81 offset:3900
	ds_read_b128 v[134:137], v11 offset:16976
	s_waitcnt vmcnt(40) lgkmcnt(1)
	v_pk_mul_f32 v[82:83], v[82:83], v[130:131]
	v_pk_mul_f32 v[84:85], v[84:85], v[132:133]
	ds_write_b32 v13, v82 offset:4160
	ds_write_b32 v13, v83 offset:4420
	ds_write_b32 v13, v84 offset:4680
	ds_write_b32 v13, v85 offset:4940
	ds_read_b128 v[130:133], v11 offset:16992
	s_waitcnt vmcnt(36) lgkmcnt(1)
	v_pk_mul_f32 v[86:87], v[86:87], v[134:135]
	v_pk_mul_f32 v[88:89], v[88:89], v[136:137]
	ds_write_b32 v13, v86 offset:5200
	ds_write_b32 v13, v87 offset:5460
	ds_write_b32 v13, v88 offset:5720
	ds_write_b32 v13, v89 offset:5980
	ds_read_b128 v[134:137], v11 offset:17008
	s_waitcnt vmcnt(32) lgkmcnt(1)
	v_pk_mul_f32 v[90:91], v[90:91], v[130:131]
	v_pk_mul_f32 v[92:93], v[92:93], v[132:133]
	ds_write_b32 v13, v90 offset:6240
	ds_write_b32 v13, v91 offset:6500
	ds_write_b32 v13, v92 offset:6760
	ds_write_b32 v13, v93 offset:7020
	ds_read_b128 v[130:133], v11 offset:17024
	s_waitcnt vmcnt(28) lgkmcnt(1)
	v_pk_mul_f32 v[94:95], v[94:95], v[134:135]
	v_pk_mul_f32 v[96:97], v[96:97], v[136:137]
	ds_write_b32 v13, v94 offset:7280
	ds_write_b32 v13, v95 offset:7540
	ds_write_b32 v13, v96 offset:7800
	ds_write_b32 v13, v97 offset:8060
	ds_read_b128 v[134:137], v11 offset:17040
	s_waitcnt vmcnt(24) lgkmcnt(1)
	v_pk_mul_f32 v[98:99], v[98:99], v[130:131]
	v_pk_mul_f32 v[100:101], v[100:101], v[132:133]
	ds_write_b32 v13, v98 offset:8320
	ds_write_b32 v13, v99 offset:8580
	ds_write_b32 v13, v100 offset:8840
	ds_write_b32 v13, v101 offset:9100
	ds_read_b128 v[130:133], v11 offset:17056
	s_waitcnt vmcnt(20) lgkmcnt(1)
	v_pk_mul_f32 v[102:103], v[102:103], v[134:135]
	v_pk_mul_f32 v[104:105], v[104:105], v[136:137]
	ds_write_b32 v13, v102 offset:9360
	ds_write_b32 v13, v103 offset:9620
	ds_write_b32 v13, v104 offset:9880
	ds_write_b32 v13, v105 offset:10140
	ds_read_b128 v[134:137], v11 offset:17072
	s_waitcnt vmcnt(16) lgkmcnt(1)
; __device__ __forceinline__ float bf2f(unsigned v) { return __uint_as_float(v << 16); }
; __device__ __forceinline__ unsigned pk2(float lo, float hi) { return pg8::cvt_pk_bf16(lo, hi); }
; template <bool SRC_BF16> __device__ __forceinline__ void tr_tile(const void* src, int stride, int col0, int myrow, float myscale, bf16_t* dst, float* wl, int lane) {
;     ...
;     for (int i = 0; i < 64; ++i) { const int r = rws[i]; float v;
;         if (SRC_BF16) v = bf2f(((const bf16_t*)src)[(size_t)r * stride + col0 + lane]); else v = ((const float*)src)[(size_t)r * stride + col0 + lane] * scs[i];
;         scr[i * 65 + lane] = v; }
;     asm volatile("s_waitcnt vmcnt(0) lgkmcnt(0)" ::: "memory");
;     const int pb = lane & 7, cl = lane >> 3, ib = 32 * (pb >> 2) + 16 * ((pb >> 1) & 1) + 4 * (pb & 1);
; #pragma unroll
;     for (int k = 0; k < 8; ++k) { const int j = cl + 8 * k; float v[8];
; #pragma unroll
;         for (int jj = 0; jj < 8; ++jj) v[jj] = scr[(ib + 8 * (jj >> 2) + (jj & 3)) * 65 + j];
;         u32x4 w; w.x = pk2(v[0], v[1]); w.y = pk2(v[2], v[3]); w.z = pk2(v[4], v[5]); w.w = pk2(v[6], v[7]);
;         *(u32x4*)(dst + (size_t)j * KVL + 8 * pb) = w; }
	v_pk_mul_f32 v[106:107], v[106:107], v[130:131]
	v_pk_mul_f32 v[108:109], v[108:109], v[132:133]
	ds_write_b32 v13, v106 offset:10400
	ds_write_b32 v13, v107 offset:10660
	ds_write_b32 v13, v108 offset:10920
	ds_write_b32 v13, v109 offset:11180
	ds_read_b128 v[130:133], v11 offset:17088
	s_waitcnt vmcnt(12) lgkmcnt(1)
	v_pk_mul_f32 v[110:111], v[110:111], v[134:135]
	v_pk_mul_f32 v[112:113], v[112:113], v[136:137]
	ds_write_b32 v13, v110 offset:11440
	ds_write_b32 v13, v111 offset:11700
	ds_write_b32 v13, v112 offset:11960
	ds_write_b32 v13, v113 offset:12220
	ds_read_b128 v[134:137], v11 offset:17104
	s_waitcnt vmcnt(8) lgkmcnt(1)
	v_pk_mul_f32 v[114:115], v[114:115], v[130:131]
	v_pk_mul_f32 v[116:117], v[116:117], v[132:133]
	ds_write_b32 v13, v114 offset:12480
	ds_write_b32 v13, v115 offset:12740
	ds_write_b32 v13, v116 offset:13000
	ds_write_b32 v13, v117 offset:13260
	ds_read_b128 v[130:133], v11 offset:17120
	s_waitcnt vmcnt(4) lgkmcnt(1)
	v_pk_mul_f32 v[118:119], v[118:119], v[134:135]
	v_pk_mul_f32 v[120:121], v[120:121], v[136:137]
	ds_write_b32 v13, v118 offset:13520
	ds_write_b32 v13, v119 offset:13780
	ds_write_b32 v13, v120 offset:14040
	ds_write_b32 v13, v121 offset:14300
	s_waitcnt vmcnt(0) lgkmcnt(0)
	v_pk_mul_f32 v[122:123], v[122:123], v[130:131]
	v_pk_mul_f32 v[124:125], v[124:125], v[132:133]
	ds_write_b32 v13, v122 offset:14560
	ds_write_b32 v13, v123 offset:14820
	ds_write_b32 v13, v124 offset:15080
	ds_write_b32 v13, v125 offset:15340
	s_waitcnt lgkmcnt(0)
	global_load_dword v126, v[2:3], off
	global_load_dword v127, v[4:5], off
	s_waitcnt lgkmcnt(0)
	v_mad_i64_i32 v[2:3], s[0:1], v30, s78, v[26:27]
	v_mad_i64_i32 v[26:27], s[0:1], v31, s78, v[26:27]
	global_load_dword v128, v[2:3], off
	s_nop 0
	global_load_dword v129, v[26:27], off
	s_mov_b32 s0, 0x11000
	v_lshl_add_u64 v[2:3], s[30:31], 0, v[0:1]
	v_lshlrev_b32_e32 v0, 1, v19
	ds_read_b128 v[134:137], v11 offset:17136
	s_waitcnt vmcnt(0) lgkmcnt(0)
	v_pk_mul_f32 v[126:127], v[126:127], v[134:135]
	v_pk_mul_f32 v[128:129], v[128:129], v[136:137]
	ds_write_b32 v13, v126 offset:15600
	ds_write_b32 v13, v127 offset:15860
	ds_write_b32 v13, v128 offset:16120
	ds_write_b32 v13, v129 offset:16380
	s_waitcnt vmcnt(0) lgkmcnt(0)
	v_add_u32_e32 v19, 0x800, v15
	ds_read2_b32 v[28:29], v15 offset0:65 offset1:73
	ds_read2_b32 v[30:31], v15 offset1:8
	ds_read2_b32 v[32:33], v15 offset0:130 offset1:138
	ds_read2_b32 v[34:35], v15 offset0:195 offset1:203
	ds_read2_b32 v[36:37], v19 offset0:8 offset1:16
	ds_read2_b32 v[38:39], v19 offset0:73 offset1:81
	ds_read2_b32 v[40:41], v19 offset0:138 offset1:146
	ds_read2_b32 v[42:43], v19 offset0:203 offset1:211
	v_lshl_add_u64 v[2:3], v[2:3], 0, v[0:1]
	v_lshlrev_b32_e32 v0, 1, v8
	v_lshl_add_u64 v[26:27], v[2:3], 0, v[0:1]
	v_lshlrev_b32_e32 v0, 1, v10
	v_lshl_add_u64 v[44:45], v[26:27], 0, v[0:1]
	s_waitcnt lgkmcnt(6)
	v_cvt_pk_bf16_f32 v2, v30, v28
	s_waitcnt lgkmcnt(4)
	v_cvt_pk_bf16_f32 v3, v32, v34
	s_waitcnt lgkmcnt(2)
	v_cvt_pk_bf16_f32 v4, v36, v38
	s_waitcnt lgkmcnt(0)
	v_cvt_pk_bf16_f32 v5, v40, v42
	v_add_co_u32_e32 v28, vcc, s0, v44
	global_store_dwordx4 v[44:45], v[2:5], off
	v_lshlrev_b32_e32 v0, 1, v12
	s_nop 0
	v_cvt_pk_bf16_f32 v2, v31, v29
	v_cvt_pk_bf16_f32 v3, v33, v35
	v_cvt_pk_bf16_f32 v4, v37, v39
	v_cvt_pk_bf16_f32 v5, v41, v43
	v_addc_co_u32_e32 v29, vcc, 0, v45, vcc
	global_store_dwordx4 v[28:29], v[2:5], off
	ds_read2_b32 v[28:29], v15 offset0:81 offset1:89
	ds_read2_b32 v[30:31], v15 offset0:16 offset1:24
	ds_read2_b32 v[32:33], v15 offset0:146 offset1:154
	ds_read2_b32 v[34:35], v15 offset0:211 offset1:219
	ds_read2_b32 v[36:37], v19 offset0:24 offset1:32
	ds_read2_b32 v[38:39], v19 offset0:89 offset1:97
	ds_read2_b32 v[40:41], v19 offset0:154 offset1:162
	ds_read2_b32 v[42:43], v19 offset0:219 offset1:227
	v_add_co_u32_e32 v46, vcc, s60, v44
	s_waitcnt lgkmcnt(6)
	v_cvt_pk_bf16_f32 v2, v30, v28
	v_addc_co_u32_e32 v47, vcc, 0, v45, vcc
	s_waitcnt lgkmcnt(4)
	v_cvt_pk_bf16_f32 v3, v32, v34
	s_waitcnt lgkmcnt(2)
	v_cvt_pk_bf16_f32 v4, v36, v38
	s_waitcnt lgkmcnt(0)
	v_cvt_pk_bf16_f32 v5, v40, v42
	v_add_co_u32_e32 v28, vcc, s25, v44
	global_store_dwordx4 v[46:47], v[2:5], off
	s_nop 1
	v_cvt_pk_bf16_f32 v2, v31, v29
	v_cvt_pk_bf16_f32 v3, v33, v35
	v_cvt_pk_bf16_f32 v4, v37, v39
	v_cvt_pk_bf16_f32 v5, v41, v43
	v_addc_co_u32_e32 v29, vcc, 0, v45, vcc
	global_store_dwordx4 v[28:29], v[2:5], off
	ds_read2_b32 v[28:29], v15 offset0:97 offset1:105
	ds_read2_b32 v[30:31], v15 offset0:32 offset1:40
	ds_read2_b32 v[32:33], v15 offset0:162 offset1:170
	ds_read2_b32 v[34:35], v15 offset0:227 offset1:235
	ds_read2_b32 v[36:37], v19 offset0:40 offset1:48
	ds_read2_b32 v[38:39], v19 offset0:105 offset1:113
	ds_read2_b32 v[40:41], v19 offset0:170 offset1:178
	ds_read2_b32 v[42:43], v19 offset0:235 offset1:243
	s_waitcnt lgkmcnt(6)
	v_cvt_pk_bf16_f32 v2, v30, v28
	s_waitcnt lgkmcnt(4)
	v_cvt_pk_bf16_f32 v3, v32, v34
	s_waitcnt lgkmcnt(2)
	v_cvt_pk_bf16_f32 v4, v36, v38
	v_lshl_add_u64 v[44:45], v[26:27], 0, v[0:1]
	s_waitcnt lgkmcnt(0)
	v_cvt_pk_bf16_f32 v5, v40, v42
	v_lshlrev_b32_e32 v0, 1, v14
	global_store_dwordx4 v[44:45], v[2:5], off
	s_nop 1
	v_cvt_pk_bf16_f32 v2, v31, v29
	v_cvt_pk_bf16_f32 v3, v33, v35
	v_cvt_pk_bf16_f32 v4, v37, v39
	v_cvt_pk_bf16_f32 v5, v41, v43
	v_lshl_add_u64 v[28:29], v[26:27], 0, v[0:1]
	global_store_dwordx4 v[28:29], v[2:5], off
	v_add_u32_e32 v0, 0xa00, v15
	ds_read2_b32 v[28:29], v15 offset0:48 offset1:56
	ds_read2_b32 v[30:31], v15 offset0:113 offset1:121
	ds_read2_b32 v[32:33], v15 offset0:178 offset1:186
	ds_read2_b32 v[34:35], v15 offset0:243 offset1:251
	ds_read2_b32 v[36:37], v19 offset0:56 offset1:64
	ds_read2_b32 v[38:39], v19 offset0:121 offset1:129
	ds_read2_b32 v[40:41], v19 offset0:186 offset1:194
	ds_read2_b32 v[42:43], v0 offset0:123 offset1:131
	v_lshlrev_b32_e32 v0, 1, v16
	s_waitcnt lgkmcnt(6)
	v_cvt_pk_bf16_f32 v2, v28, v30
	s_waitcnt lgkmcnt(4)
	v_cvt_pk_bf16_f32 v3, v32, v34
	s_waitcnt lgkmcnt(2)
	v_cvt_pk_bf16_f32 v4, v36, v38
	s_waitcnt lgkmcnt(0)
	v_cvt_pk_bf16_f32 v5, v40, v42
	v_lshl_add_u64 v[44:45], v[26:27], 0, v[0:1]
	v_lshlrev_b32_e32 v0, 1, v18
	global_store_dwordx4 v[44:45], v[2:5], off
	v_lshl_add_u64 v[26:27], v[26:27], 0, v[0:1]
	s_nop 0
	v_cvt_pk_bf16_f32 v2, v29, v31
	v_cvt_pk_bf16_f32 v3, v33, v35
	v_cvt_pk_bf16_f32 v4, v37, v39
	v_cvt_pk_bf16_f32 v5, v41, v43
	global_store_dwordx4 v[26:27], v[2:5], off
	s_waitcnt lgkmcnt(0)
